# epilogue loads hoisted (G1e/G1o/G3 rowsq both rows up front, G2 xb second half up front) + attention V tiles 0/1 requested at task top
# speedup vs baseline: 1.0118x; 1.0021x over previous
; #define AT32_QK(t0, t1) do { _Pragma("unroll") for (int tile = (t0); tile < (t1); ++tile) { f32x16 z; _Pragma("unroll") for (int e = 0; e < 16; ++e) z[e] = 0.f; \
;         _Pragma("unroll") for (int ds = 0; ds < 4; ++ds) z = __builtin_amdgcn_mfma_f32_32x32x16_bf16(kf[tile][ds], qf[ds], z, 0, 0, 0); s[tile] = z; } } while (0)
; __device__ __forceinline__ void at_task32(const Args& A, const At32& T, const At32& Tn, bf16x8 (&qf)[4], bf16x8 (&kf)[5][4], LAS unsigned char* lds, LAS unsigned char* vst, int lane) {
;     ...
;     f32x16 s[5];
;     ...
;     AT32_QK(0, 3);
;     __builtin_amdgcn_sched_barrier(0);
;     AT32_QK(3, 5);
;     __builtin_amdgcn_sched_barrier(0);
;     ...
; #pragma unroll
;     for (int e = 0; e < 16; ++e) { const int cr = (e & 3) + 8 * (e >> 2) + 4 * h; if (cr - q32 < 0) s[0][e] = -1e30f; if (128 + cr - q32 > 128) s[4][e] = -1e30f; }
;     if (lk0 < 0 || lk0 + 159 >= L) {
;     ...
;     for (int idx = 0; idx < 8; ++idx) { const int row = 8 * idx + (lane >> 3); int lk = lk0 + row; lk = lk < 0 ? 0 : (lk > L - 1 ? L - 1 : lk);
;         vr[idx] = *(const u32x4*)(Vb + ((unsigned)((lk << dsh) + r) * 2048u + 16u * (lane & 7))); }
.LBB0_405:
	v_readlane_b32 s100, v253, 58
	v_readlane_b32 s101, v253, 59
	s_ashr_i32 s98, s22, 4
	s_lshl_b32 s98, s98, 24
	s_lshl_b32 s99, s22, 7
	s_and_b32 s99, s99, 0x780
	s_add_u32 s98, s98, s99
	s_add_u32 s100, s100, s98
	s_addc_u32 s101, s101, 0
	s_lshr_b32 s99, 0x2000, s27
	s_add_i32 s99, s99, -1
	s_sub_i32 s98, s3, 64
	v_add_u32_e32 v211, s98, v172
	v_med3_i32 v242, v211, 0, s99
	v_lshlrev_b32_e32 v242, s27, v242
	v_add_u32_e32 v242, s31, v242
	v_lshl_or_b32 v242, v242, 11, v173
	global_load_dwordx4 v[212:215], v242, s[100:101]
	v_add_u32_e32 v243, 8, v211
	v_med3_i32 v243, v243, 0, s99
	v_lshlrev_b32_e32 v243, s27, v243
	v_add_u32_e32 v243, s31, v243
	v_lshl_or_b32 v243, v243, 11, v173
	global_load_dwordx4 v[216:219], v243, s[100:101]
	v_add_u32_e32 v242, 16, v211
	v_med3_i32 v242, v242, 0, s99
	v_lshlrev_b32_e32 v242, s27, v242
	v_add_u32_e32 v242, s31, v242
	v_lshl_or_b32 v242, v242, 11, v173
	global_load_dwordx4 v[220:223], v242, s[100:101]
	v_add_u32_e32 v243, 24, v211
	v_med3_i32 v243, v243, 0, s99
	v_lshlrev_b32_e32 v243, s27, v243
	v_add_u32_e32 v243, s31, v243
	v_lshl_or_b32 v243, v243, 11, v173
	global_load_dwordx4 v[224:227], v243, s[100:101]
	v_add_u32_e32 v242, 32, v211
	v_med3_i32 v242, v242, 0, s99
	v_lshlrev_b32_e32 v242, s27, v242
	v_add_u32_e32 v242, s31, v242
	v_lshl_or_b32 v242, v242, 11, v173
	global_load_dwordx4 v[228:231], v242, s[100:101]
	v_add_u32_e32 v243, 40, v211
	v_med3_i32 v243, v243, 0, s99
	v_lshlrev_b32_e32 v243, s27, v243
	v_add_u32_e32 v243, s31, v243
	v_lshl_or_b32 v243, v243, 11, v173
	global_load_dwordx4 v[232:235], v243, s[100:101]
	v_add_u32_e32 v242, 48, v211
	v_med3_i32 v242, v242, 0, s99
	v_lshlrev_b32_e32 v242, s27, v242
	v_add_u32_e32 v242, s31, v242
	v_lshl_or_b32 v242, v242, 11, v173
	global_load_dwordx4 v[248:251], v242, s[100:101]
	v_add_u32_e32 v243, 56, v211
	v_med3_i32 v243, v243, 0, s99
	v_lshlrev_b32_e32 v243, s27, v243
	v_add_u32_e32 v243, s31, v243
	v_lshl_or_b32 v243, v243, 11, v173
	global_load_dwordx4 v[236:239], v243, s[100:101]
	s_waitcnt vmcnt(8)
	v_mfma_f32_32x32x16_bf16 v[78:93], v[32:35], v[68:71], 0
	s_lshr_b32 s34, 0x2000, s27
	v_mfma_f32_32x32x16_bf16 v[78:93], v[36:39], v[72:75], v[78:93]
	v_mfma_f32_32x32x16_bf16 v[78:93], v[40:43], v[94:97], v[78:93]
	v_mfma_f32_32x32x16_bf16 v[78:93], v[44:47], v[64:67], v[78:93]
	v_mfma_f32_32x32x16_bf16 v[48:63], v[48:51], v[68:71], 0
	v_mfma_f32_32x32x16_bf16 v[32:47], v[114:117], v[68:71], 0
	v_mfma_f32_32x32x16_bf16 v[48:63], v[98:101], v[72:75], v[48:63]
	v_mfma_f32_32x32x16_bf16 v[32:47], v[118:121], v[72:75], v[32:47]
	v_mfma_f32_32x32x16_bf16 v[48:63], v[102:105], v[94:97], v[48:63]
	v_mfma_f32_32x32x16_bf16 v[32:47], v[122:125], v[94:97], v[32:47]
	v_mfma_f32_32x32x16_bf16 v[48:63], v[106:109], v[64:67], v[48:63]
	v_mfma_f32_32x32x16_bf16 v[32:47], v[110:113], v[64:67], v[32:47]
	v_mfma_f32_32x32x16_bf16 v[16:31], v[126:129], v[68:71], 0
	s_sub_i32 s35, s3, 64
	v_mfma_f32_32x32x16_bf16 v[0:15], v[146:149], v[68:71], 0
	v_mfma_f32_32x32x16_bf16 v[16:31], v[130:133], v[72:75], v[16:31]
	v_mfma_f32_32x32x16_bf16 v[0:15], v[150:153], v[72:75], v[0:15]
	v_mfma_f32_32x32x16_bf16 v[16:31], v[134:137], v[94:97], v[16:31]
	v_mfma_f32_32x32x16_bf16 v[0:15], v[154:157], v[94:97], v[0:15]
	v_mfma_f32_32x32x16_bf16 v[16:31], v[138:141], v[64:67], v[16:31]
	v_mfma_f32_32x32x16_bf16 v[0:15], v[142:145], v[64:67], v[0:15]
	s_cmp_gt_i32 s3, 63
	s_cselect_b64 s[6:7], -1, 0
	s_add_i32 vcc_lo, s3, 0x5f
	s_cmp_lt_i32 vcc_lo, s34
	s_cselect_b64 vcc, -1, 0
	s_and_b64 s[6:7], s[6:7], vcc
	v_cndmask_b32_e64 v78, v78, v246, s[38:39]
	v_cndmask_b32_e64 v79, v79, v246, s[42:43]
	v_cndmask_b32_e64 v76, v80, v246, s[46:47]
	v_cndmask_b32_e64 v77, v81, v246, s[50:51]
	v_cndmask_b32_e64 v74, v82, v246, s[54:55]
	v_cndmask_b32_e64 v75, v83, v246, s[58:59]
	v_cndmask_b32_e64 v72, v84, v246, s[62:63]
	v_cndmask_b32_e64 v73, v85, v246, s[66:67]
	v_cndmask_b32_e64 v70, v86, v246, s[70:71]
	v_cndmask_b32_e64 v71, v87, v246, s[74:75]
	v_cndmask_b32_e64 v68, v88, v246, s[78:79]
	v_cndmask_b32_e64 v69, v89, v246, s[82:83]
	v_cndmask_b32_e64 v66, v90, v246, s[86:87]
	v_cndmask_b32_e64 v67, v91, v246, s[90:91]
	v_cndmask_b32_e64 v64, v92, v246, s[94:95]
	v_cndmask_b32_e64 v65, v93, v246, s[0:1]
	v_cndmask_b32_e64 v0, v0, v246, s[40:41]
	v_cndmask_b32_e64 v1, v1, v246, s[44:45]
	v_cndmask_b32_e64 v2, v2, v246, s[48:49]
	v_cndmask_b32_e64 v3, v3, v246, s[52:53]
	v_cndmask_b32_e64 v4, v4, v246, s[56:57]
	v_cndmask_b32_e64 v5, v5, v246, s[60:61]
	v_cndmask_b32_e64 v6, v6, v246, s[64:65]
	v_cndmask_b32_e64 v7, v7, v246, s[68:69]
	v_cndmask_b32_e64 v8, v8, v246, s[72:73]
	v_cndmask_b32_e64 v9, v9, v246, s[76:77]
	v_cndmask_b32_e64 v10, v10, v246, s[80:81]
	v_cndmask_b32_e64 v11, v11, v246, s[84:85]
	v_cndmask_b32_e64 v12, v12, v246, s[88:89]
	v_cndmask_b32_e64 v13, v13, v246, s[92:93]
	v_cndmask_b32_e64 v14, v14, v246, s[96:97]
	v_cndmask_b32_e64 v15, v15, v246, s[8:9]
	s_and_b64 vcc, exec, s[6:7]
	s_cbranch_vccnz .LBB0_407
; __device__ __forceinline__ void at_task32(const Args& A, const At32& T, const At32& Tn, bf16x8 (&qf)[4], bf16x8 (&kf)[5][4], LAS unsigned char* lds, LAS unsigned char* vst, int lane) {
;     ...
;     if (lk0 < 0 || lk0 + 159 >= L) {
; #pragma unroll
;         for (int tile = 0; tile < 5; ++tile)
; #pragma unroll
;             for (int e = 0; e < 16; ++e) { const int lk = lk0 + 32 * tile + (e & 3) + 8 * (e >> 2) + 4 * h; if (lk < 0 || lk >= L) s[tile][e] = -1e30f; }
;     }
	v_add_u32_e32 v80, s35, v171
	v_cmp_lt_i32_e32 vcc, -1, v80
	v_cmp_gt_i32_e64 s[6:7], s34, v80
	s_and_b64 vcc, vcc, s[6:7]
	v_add_u32_e32 v81, 1, v80
	v_cndmask_b32_e32 v78, v246, v78, vcc
	v_cmp_lt_i32_e32 vcc, -2, v80
	v_cmp_gt_i32_e64 s[6:7], s34, v81
	s_and_b64 vcc, vcc, s[6:7]
	v_add_u32_e32 v81, 2, v80
	v_cndmask_b32_e32 v79, v246, v79, vcc
	v_cmp_lt_i32_e32 vcc, -3, v80
	v_cmp_gt_i32_e64 s[6:7], s34, v81
	s_and_b64 vcc, vcc, s[6:7]
	v_add_u32_e32 v81, 3, v80
	v_cndmask_b32_e32 v76, v246, v76, vcc
	v_cmp_lt_i32_e32 vcc, -4, v80
	v_cmp_gt_i32_e64 s[6:7], s34, v81
	s_and_b64 vcc, vcc, s[6:7]
	v_add_u32_e32 v81, 8, v80
	v_cndmask_b32_e32 v77, v246, v77, vcc
	v_cmp_lt_i32_e32 vcc, -9, v80
	v_cmp_gt_i32_e64 s[6:7], s34, v81
	s_and_b64 vcc, vcc, s[6:7]
	v_add_u32_e32 v81, 9, v80
	v_cndmask_b32_e32 v74, v246, v74, vcc
	v_cmp_lt_i32_e32 vcc, -10, v80
	v_cmp_gt_i32_e64 s[6:7], s34, v81
	s_and_b64 vcc, vcc, s[6:7]
	v_add_u32_e32 v81, 10, v80
	v_cndmask_b32_e32 v75, v246, v75, vcc
	v_cmp_lt_i32_e32 vcc, -11, v80
	v_cmp_gt_i32_e64 s[6:7], s34, v81
	s_and_b64 vcc, vcc, s[6:7]
	v_add_u32_e32 v81, 11, v80
	v_cndmask_b32_e32 v72, v246, v72, vcc
	v_cmp_lt_i32_e32 vcc, -12, v80
	v_cmp_gt_i32_e64 s[6:7], s34, v81
	s_and_b64 vcc, vcc, s[6:7]
	v_add_u32_e32 v81, 16, v80
	s_movk_i32 s19, 0xffef
	v_cndmask_b32_e32 v73, v246, v73, vcc
	v_cmp_lt_i32_e32 vcc, s19, v80
	v_cmp_gt_i32_e64 s[6:7], s34, v81
	s_and_b64 vcc, vcc, s[6:7]
	v_add_u32_e32 v81, 17, v80
	s_movk_i32 s6, 0xffee
	v_cndmask_b32_e32 v70, v246, v70, vcc
	v_cmp_lt_i32_e32 vcc, s6, v80
	v_cmp_gt_i32_e64 s[6:7], s34, v81
	s_and_b64 vcc, vcc, s[6:7]
	v_add_u32_e32 v81, 18, v80
	s_movk_i32 s6, 0xffed
	v_cndmask_b32_e32 v71, v246, v71, vcc
	v_cmp_lt_i32_e32 vcc, s6, v80
	v_cmp_gt_i32_e64 s[6:7], s34, v81
	s_and_b64 vcc, vcc, s[6:7]
	v_add_u32_e32 v81, 19, v80
	s_movk_i32 s6, 0xffec
	v_cndmask_b32_e32 v68, v246, v68, vcc
	v_cmp_lt_i32_e32 vcc, s6, v80
	v_cmp_gt_i32_e64 s[6:7], s34, v81
	s_and_b64 vcc, vcc, s[6:7]
	v_add_u32_e32 v81, 24, v80
	s_movk_i32 s12, 0xffe7
	v_cndmask_b32_e32 v69, v246, v69, vcc
	v_cmp_lt_i32_e32 vcc, s12, v80
	v_cmp_gt_i32_e64 s[6:7], s34, v81
	s_and_b64 vcc, vcc, s[6:7]
	v_add_u32_e32 v81, 25, v80
	s_movk_i32 s6, 0xffe6
	v_cndmask_b32_e32 v66, v246, v66, vcc
	v_cmp_lt_i32_e32 vcc, s6, v80
	v_cmp_gt_i32_e64 s[6:7], s34, v81
	s_and_b64 vcc, vcc, s[6:7]
	v_add_u32_e32 v81, 26, v80
	s_movk_i32 s6, 0xffe5
	v_cndmask_b32_e32 v67, v246, v67, vcc
	v_cmp_lt_i32_e32 vcc, s6, v80
	v_cmp_gt_i32_e64 s[6:7], s34, v81
	s_and_b64 vcc, vcc, s[6:7]
	v_add_u32_e32 v81, 27, v80
	s_movk_i32 s6, 0xffe4
	v_cndmask_b32_e32 v64, v246, v64, vcc
	v_cmp_lt_i32_e32 vcc, s6, v80
	v_cmp_gt_i32_e64 s[6:7], s34, v81
	s_and_b64 vcc, vcc, s[6:7]
	v_add_u32_e32 v81, 32, v80
	v_cndmask_b32_e32 v65, v246, v65, vcc
	v_cmp_lt_i32_e32 vcc, s13, v80
	v_cmp_gt_i32_e64 s[6:7], s34, v81
	s_and_b64 vcc, vcc, s[6:7]
	v_add_u32_e32 v81, 33, v80
	s_movk_i32 s6, 0xffde
	v_cndmask_b32_e32 v48, v246, v48, vcc
	v_cmp_lt_i32_e32 vcc, s6, v80
	v_cmp_gt_i32_e64 s[6:7], s34, v81
	s_and_b64 vcc, vcc, s[6:7]
	v_add_u32_e32 v81, 34, v80
	s_movk_i32 s6, 0xffdd
	v_cndmask_b32_e32 v49, v246, v49, vcc
	v_cmp_lt_i32_e32 vcc, s6, v80
	v_cmp_gt_i32_e64 s[6:7], s34, v81
	s_and_b64 vcc, vcc, s[6:7]
	v_add_u32_e32 v81, 35, v80
	s_movk_i32 s6, 0xffdc
	v_cndmask_b32_e32 v50, v246, v50, vcc
	v_cmp_lt_i32_e32 vcc, s6, v80
	v_cmp_gt_i32_e64 s[6:7], s34, v81
	s_and_b64 vcc, vcc, s[6:7]
	v_add_u32_e32 v81, 40, v80
	s_movk_i32 s29, 0xffd7
	v_cndmask_b32_e32 v51, v246, v51, vcc
	v_cmp_lt_i32_e32 vcc, s29, v80
	v_cmp_gt_i32_e64 s[6:7], s34, v81
	s_and_b64 vcc, vcc, s[6:7]
	v_add_u32_e32 v81, 41, v80
	s_movk_i32 s6, 0xffd6
	v_cndmask_b32_e32 v52, v246, v52, vcc
	v_cmp_lt_i32_e32 vcc, s6, v80
	v_cmp_gt_i32_e64 s[6:7], s34, v81
	s_and_b64 vcc, vcc, s[6:7]
	v_add_u32_e32 v81, 42, v80
	s_movk_i32 s6, 0xffd5
	v_cndmask_b32_e32 v53, v246, v53, vcc
	v_cmp_lt_i32_e32 vcc, s6, v80
	v_cmp_gt_i32_e64 s[6:7], s34, v81
	s_and_b64 vcc, vcc, s[6:7]
	v_add_u32_e32 v81, 43, v80
	s_movk_i32 s6, 0xffd4
	v_cndmask_b32_e32 v54, v246, v54, vcc
	v_cmp_lt_i32_e32 vcc, s6, v80
	v_cmp_gt_i32_e64 s[6:7], s34, v81
	s_and_b64 vcc, vcc, s[6:7]
	v_add_u32_e32 v81, 48, v80
	s_movk_i32 s2, 0xffcf
	v_cndmask_b32_e32 v55, v246, v55, vcc
	v_cmp_lt_i32_e32 vcc, s2, v80
	v_cmp_gt_i32_e64 s[6:7], s34, v81
	s_and_b64 vcc, vcc, s[6:7]
	v_add_u32_e32 v81, 49, v80
	s_movk_i32 s6, 0xffce
	v_cndmask_b32_e32 v56, v246, v56, vcc
	v_cmp_lt_i32_e32 vcc, s6, v80
	v_cmp_gt_i32_e64 s[6:7], s34, v81
	s_and_b64 vcc, vcc, s[6:7]
	v_add_u32_e32 v81, 50, v80
	s_movk_i32 s6, 0xffcd
	v_cndmask_b32_e32 v57, v246, v57, vcc
	v_cmp_lt_i32_e32 vcc, s6, v80
	v_cmp_gt_i32_e64 s[6:7], s34, v81
	s_and_b64 vcc, vcc, s[6:7]
	v_add_u32_e32 v81, 51, v80
	s_movk_i32 s6, 0xffcc
	v_cndmask_b32_e32 v58, v246, v58, vcc
	v_cmp_lt_i32_e32 vcc, s6, v80
	v_cmp_gt_i32_e64 s[6:7], s34, v81
	s_and_b64 vcc, vcc, s[6:7]
	v_add_u32_e32 v81, 56, v80
	s_movk_i32 s18, 0xffc7
	v_cndmask_b32_e32 v59, v246, v59, vcc
	v_cmp_lt_i32_e32 vcc, s18, v80
	v_cmp_gt_i32_e64 s[6:7], s34, v81
	s_and_b64 vcc, vcc, s[6:7]
	v_add_u32_e32 v81, 57, v80
	s_movk_i32 s6, 0xffc6
	v_cndmask_b32_e32 v60, v246, v60, vcc
	v_cmp_lt_i32_e32 vcc, s6, v80
	v_cmp_gt_i32_e64 s[6:7], s34, v81
	s_and_b64 vcc, vcc, s[6:7]
	v_add_u32_e32 v81, 58, v80
	s_movk_i32 s6, 0xffc5
	v_cndmask_b32_e32 v61, v246, v61, vcc
	v_cmp_lt_i32_e32 vcc, s6, v80
	v_cmp_gt_i32_e64 s[6:7], s34, v81
	s_and_b64 vcc, vcc, s[6:7]
	v_add_u32_e32 v81, 59, v80
	s_movk_i32 s6, 0xffc4
	v_cndmask_b32_e32 v62, v246, v62, vcc
	v_cmp_lt_i32_e32 vcc, s6, v80
	v_cmp_gt_i32_e64 s[6:7], s34, v81
	s_and_b64 vcc, vcc, s[6:7]
; __device__ __forceinline__ void at_task32(const Args& A, const At32& T, const At32& Tn, bf16x8 (&qf)[4], bf16x8 (&kf)[5][4], LAS unsigned char* lds, LAS unsigned char* vst, int lane) {
;     ...
;     if (lk0 < 0 || lk0 + 159 >= L) {
; #pragma unroll
;         for (int tile = 0; tile < 5; ++tile)
; #pragma unroll
;             for (int e = 0; e < 16; ++e) { const int lk = lk0 + 32 * tile + (e & 3) + 8 * (e >> 2) + 4 * h; if (lk < 0 || lk >= L) s[tile][e] = -1e30f; }
;     }
	v_add_u32_e32 v81, s3, v171
	v_cndmask_b32_e32 v63, v246, v63, vcc
	v_cmp_lt_i32_e32 vcc, -1, v81
	v_cmp_gt_i32_e64 s[6:7], s34, v81
	s_and_b64 vcc, vcc, s[6:7]
	v_add_u32_e32 v81, 0x41, v80
	s_movk_i32 s6, 0xffbe
	v_cndmask_b32_e32 v32, v246, v32, vcc
	v_cmp_lt_i32_e32 vcc, s6, v80
	v_cmp_gt_i32_e64 s[6:7], s34, v81
	s_and_b64 vcc, vcc, s[6:7]
	v_add_u32_e32 v81, 0x42, v80
	s_movk_i32 s6, 0xffbd
	v_cndmask_b32_e32 v33, v246, v33, vcc
	v_cmp_lt_i32_e32 vcc, s6, v80
	v_cmp_gt_i32_e64 s[6:7], s34, v81
	s_and_b64 vcc, vcc, s[6:7]
	v_add_u32_e32 v81, 0x43, v80
	s_movk_i32 s6, 0xffbc
	v_cndmask_b32_e32 v34, v246, v34, vcc
	v_cmp_lt_i32_e32 vcc, s6, v80
	v_cmp_gt_i32_e64 s[6:7], s34, v81
	s_and_b64 vcc, vcc, s[6:7]
	v_add_u32_e32 v81, 0x48, v80
	s_movk_i32 s20, 0xffb7
	v_cndmask_b32_e32 v35, v246, v35, vcc
	v_cmp_lt_i32_e32 vcc, s20, v80
	v_cmp_gt_i32_e64 s[6:7], s34, v81
	s_and_b64 vcc, vcc, s[6:7]
	v_add_u32_e32 v81, 0x49, v80
	s_movk_i32 s6, 0xffb6
	v_cndmask_b32_e32 v36, v246, v36, vcc
	v_cmp_lt_i32_e32 vcc, s6, v80
	v_cmp_gt_i32_e64 s[6:7], s34, v81
	s_and_b64 vcc, vcc, s[6:7]
	v_add_u32_e32 v81, 0x4a, v80
	s_movk_i32 s6, 0xffb5
	v_cndmask_b32_e32 v37, v246, v37, vcc
	v_cmp_lt_i32_e32 vcc, s6, v80
	v_cmp_gt_i32_e64 s[6:7], s34, v81
	s_and_b64 vcc, vcc, s[6:7]
	v_add_u32_e32 v81, 0x4b, v80
	s_movk_i32 s6, 0xffb4
	v_cndmask_b32_e32 v38, v246, v38, vcc
	v_cmp_lt_i32_e32 vcc, s6, v80
	v_cmp_gt_i32_e64 s[6:7], s34, v81
	s_and_b64 vcc, vcc, s[6:7]
	v_add_u32_e32 v81, 0x50, v80
	s_movk_i32 s13, 0xffaf
	v_cndmask_b32_e32 v39, v246, v39, vcc
	v_cmp_lt_i32_e32 vcc, s13, v80
	v_cmp_gt_i32_e64 s[6:7], s34, v81
	s_and_b64 vcc, vcc, s[6:7]
	v_add_u32_e32 v81, 0x51, v80
	s_movk_i32 s6, 0xffae
	v_cndmask_b32_e32 v40, v246, v40, vcc
	v_cmp_lt_i32_e32 vcc, s6, v80
	v_cmp_gt_i32_e64 s[6:7], s34, v81
	s_and_b64 vcc, vcc, s[6:7]
	v_add_u32_e32 v81, 0x52, v80
	s_movk_i32 s6, 0xffad
	v_cndmask_b32_e32 v41, v246, v41, vcc
	v_cmp_lt_i32_e32 vcc, s6, v80
	v_cmp_gt_i32_e64 s[6:7], s34, v81
	s_and_b64 vcc, vcc, s[6:7]
	v_add_u32_e32 v81, 0x53, v80
	s_movk_i32 s6, 0xffac
	v_cndmask_b32_e32 v42, v246, v42, vcc
	v_cmp_lt_i32_e32 vcc, s6, v80
	v_cmp_gt_i32_e64 s[6:7], s34, v81
	s_and_b64 vcc, vcc, s[6:7]
	v_add_u32_e32 v81, 0x58, v80
	s_movk_i32 s15, 0xffa7
	v_cndmask_b32_e32 v43, v246, v43, vcc
	v_cmp_lt_i32_e32 vcc, s15, v80
	v_cmp_gt_i32_e64 s[6:7], s34, v81
	s_and_b64 vcc, vcc, s[6:7]
	v_add_u32_e32 v81, 0x59, v80
	s_movk_i32 s6, 0xffa6
	v_cndmask_b32_e32 v44, v246, v44, vcc
	v_cmp_lt_i32_e32 vcc, s6, v80
	v_cmp_gt_i32_e64 s[6:7], s34, v81
	s_and_b64 vcc, vcc, s[6:7]
	v_add_u32_e32 v81, 0x5a, v80
	s_movk_i32 s6, 0xffa5
	v_cndmask_b32_e32 v45, v246, v45, vcc
	v_cmp_lt_i32_e32 vcc, s6, v80
	v_cmp_gt_i32_e64 s[6:7], s34, v81
	s_and_b64 vcc, vcc, s[6:7]
	v_add_u32_e32 v81, 0x5b, v80
	s_movk_i32 s6, 0xffa4
	v_cndmask_b32_e32 v46, v246, v46, vcc
	v_cmp_lt_i32_e32 vcc, s6, v80
	v_cmp_gt_i32_e64 s[6:7], s34, v81
	s_and_b64 vcc, vcc, s[6:7]
	v_add_u32_e32 v81, 0x60, v80
	s_movk_i32 s6, 0xff9f
	v_cndmask_b32_e32 v47, v246, v47, vcc
	v_cmp_lt_i32_e32 vcc, s6, v80
	v_cmp_gt_i32_e64 s[6:7], s34, v81
	s_and_b64 vcc, vcc, s[6:7]
	v_add_u32_e32 v81, 0x61, v80
	s_movk_i32 s6, 0xff9e
	v_cndmask_b32_e32 v16, v246, v16, vcc
	v_cmp_lt_i32_e32 vcc, s6, v80
	v_cmp_gt_i32_e64 s[6:7], s34, v81
	s_and_b64 vcc, vcc, s[6:7]
	v_add_u32_e32 v81, 0x62, v80
	s_movk_i32 s6, 0xff9d
	v_cndmask_b32_e32 v17, v246, v17, vcc
	v_cmp_lt_i32_e32 vcc, s6, v80
	v_cmp_gt_i32_e64 s[6:7], s34, v81
	s_and_b64 vcc, vcc, s[6:7]
	v_add_u32_e32 v81, 0x63, v80
	s_movk_i32 s6, 0xff9c
	v_cndmask_b32_e32 v18, v246, v18, vcc
	v_cmp_lt_i32_e32 vcc, s6, v80
	v_cmp_gt_i32_e64 s[6:7], s34, v81
	s_and_b64 vcc, vcc, s[6:7]
	v_add_u32_e32 v81, 0x68, v80
	s_movk_i32 s6, 0xff97
	v_cndmask_b32_e32 v19, v246, v19, vcc
	v_cmp_lt_i32_e32 vcc, s6, v80
	v_cmp_gt_i32_e64 s[6:7], s34, v81
	s_and_b64 vcc, vcc, s[6:7]
	v_add_u32_e32 v81, 0x69, v80
	s_movk_i32 s6, 0xff96
	v_cndmask_b32_e32 v20, v246, v20, vcc
	v_cmp_lt_i32_e32 vcc, s6, v80
	v_cmp_gt_i32_e64 s[6:7], s34, v81
	s_and_b64 vcc, vcc, s[6:7]
	v_add_u32_e32 v81, 0x6a, v80
	s_movk_i32 s6, 0xff95
	v_cndmask_b32_e32 v21, v246, v21, vcc
	v_cmp_lt_i32_e32 vcc, s6, v80
	v_cmp_gt_i32_e64 s[6:7], s34, v81
	s_and_b64 vcc, vcc, s[6:7]
	v_add_u32_e32 v81, 0x6b, v80
	s_movk_i32 s6, 0xff94
	v_cndmask_b32_e32 v22, v246, v22, vcc
	v_cmp_lt_i32_e32 vcc, s6, v80
	v_cmp_gt_i32_e64 s[6:7], s34, v81
	s_and_b64 vcc, vcc, s[6:7]
	v_add_u32_e32 v81, 0x70, v80
; __device__ __forceinline__ void at_task32(const Args& A, const At32& T, const At32& Tn, bf16x8 (&qf)[4], bf16x8 (&kf)[5][4], LAS unsigned char* lds, LAS unsigned char* vst, int lane) {
;     ...
;     if (lk0 < 0 || lk0 + 159 >= L) {
; #pragma unroll
;         for (int tile = 0; tile < 5; ++tile)
; #pragma unroll
;             for (int e = 0; e < 16; ++e) { const int lk = lk0 + 32 * tile + (e & 3) + 8 * (e >> 2) + 4 * h; if (lk < 0 || lk >= L) s[tile][e] = -1e30f; }
;     }
	s_movk_i32 s6, 0xff8f
	v_cndmask_b32_e32 v23, v246, v23, vcc
	v_cmp_lt_i32_e32 vcc, s6, v80
	v_cmp_gt_i32_e64 s[6:7], s34, v81
	s_and_b64 vcc, vcc, s[6:7]
	v_add_u32_e32 v81, 0x71, v80
	s_movk_i32 s6, 0xff8e
	v_cndmask_b32_e32 v24, v246, v24, vcc
	v_cmp_lt_i32_e32 vcc, s6, v80
	v_cmp_gt_i32_e64 s[6:7], s34, v81
	s_and_b64 vcc, vcc, s[6:7]
	v_add_u32_e32 v81, 0x72, v80
	s_movk_i32 s6, 0xff8d
	v_cndmask_b32_e32 v25, v246, v25, vcc
	v_cmp_lt_i32_e32 vcc, s6, v80
	v_cmp_gt_i32_e64 s[6:7], s34, v81
	s_and_b64 vcc, vcc, s[6:7]
	v_add_u32_e32 v81, 0x73, v80
	s_movk_i32 s6, 0xff8c
	v_cndmask_b32_e32 v26, v246, v26, vcc
	v_cmp_lt_i32_e32 vcc, s6, v80
	v_cmp_gt_i32_e64 s[6:7], s34, v81
	s_and_b64 vcc, vcc, s[6:7]
	v_add_u32_e32 v81, 0x78, v80
	s_movk_i32 s6, 0xff87
	v_cndmask_b32_e32 v27, v246, v27, vcc
	v_cmp_lt_i32_e32 vcc, s6, v80
	v_cmp_gt_i32_e64 s[6:7], s34, v81
	s_and_b64 vcc, vcc, s[6:7]
	v_add_u32_e32 v81, 0x79, v80
	s_movk_i32 s6, 0xff86
	v_cndmask_b32_e32 v28, v246, v28, vcc
	v_cmp_lt_i32_e32 vcc, s6, v80
	v_cmp_gt_i32_e64 s[6:7], s34, v81
	s_and_b64 vcc, vcc, s[6:7]
	v_add_u32_e32 v81, 0x7a, v80
	s_movk_i32 s6, 0xff85
	v_cndmask_b32_e32 v29, v246, v29, vcc
	v_cmp_lt_i32_e32 vcc, s6, v80
	v_cmp_gt_i32_e64 s[6:7], s34, v81
	s_and_b64 vcc, vcc, s[6:7]
	v_add_u32_e32 v81, 0x7b, v80
	s_movk_i32 s6, 0xff84
	v_cndmask_b32_e32 v30, v246, v30, vcc
	v_cmp_lt_i32_e32 vcc, s6, v80
	v_cmp_gt_i32_e64 s[6:7], s34, v81
	s_and_b64 vcc, vcc, s[6:7]
	v_add_u32_e32 v81, 0x80, v80
	s_movk_i32 s6, 0xff7f
	v_cndmask_b32_e32 v31, v246, v31, vcc
	v_cmp_lt_i32_e32 vcc, s6, v80
	v_cmp_gt_i32_e64 s[6:7], s34, v81
	s_and_b64 vcc, vcc, s[6:7]
	v_add_u32_e32 v81, 0x81, v80
	s_movk_i32 s6, 0xff7e
	v_cndmask_b32_e32 v0, v246, v0, vcc
	v_cmp_lt_i32_e32 vcc, s6, v80
	v_cmp_gt_i32_e64 s[6:7], s34, v81
	s_and_b64 vcc, vcc, s[6:7]
	v_add_u32_e32 v81, 0x82, v80
	s_movk_i32 s6, 0xff7d
	v_cndmask_b32_e32 v1, v246, v1, vcc
	v_cmp_lt_i32_e32 vcc, s6, v80
	v_cmp_gt_i32_e64 s[6:7], s34, v81
	s_and_b64 vcc, vcc, s[6:7]
	v_add_u32_e32 v81, 0x83, v80
	s_movk_i32 s6, 0xff7c
	v_cndmask_b32_e32 v2, v246, v2, vcc
	v_cmp_lt_i32_e32 vcc, s6, v80
	v_cmp_gt_i32_e64 s[6:7], s34, v81
	s_and_b64 vcc, vcc, s[6:7]
	v_add_u32_e32 v81, 0x88, v80
	s_movk_i32 s6, 0xff77
	v_cndmask_b32_e32 v3, v246, v3, vcc
	v_cmp_lt_i32_e32 vcc, s6, v80
	v_cmp_gt_i32_e64 s[6:7], s34, v81
	s_and_b64 vcc, vcc, s[6:7]
	v_add_u32_e32 v81, 0x89, v80
	s_movk_i32 s6, 0xff76
	v_cndmask_b32_e32 v4, v246, v4, vcc
	v_cmp_lt_i32_e32 vcc, s6, v80
	v_cmp_gt_i32_e64 s[6:7], s34, v81
	s_and_b64 vcc, vcc, s[6:7]
	v_add_u32_e32 v81, 0x8a, v80
	s_movk_i32 s6, 0xff75
	v_cndmask_b32_e32 v5, v246, v5, vcc
	v_cmp_lt_i32_e32 vcc, s6, v80
	v_cmp_gt_i32_e64 s[6:7], s34, v81
	s_and_b64 vcc, vcc, s[6:7]
	v_add_u32_e32 v81, 0x8b, v80
	s_movk_i32 s6, 0xff74
	v_cndmask_b32_e32 v6, v246, v6, vcc
	v_cmp_lt_i32_e32 vcc, s6, v80
	v_cmp_gt_i32_e64 s[6:7], s34, v81
	s_and_b64 vcc, vcc, s[6:7]
	v_add_u32_e32 v81, 0x90, v80
	s_movk_i32 s6, 0xff6f
	v_cndmask_b32_e32 v7, v246, v7, vcc
	v_cmp_lt_i32_e32 vcc, s6, v80
	v_cmp_gt_i32_e64 s[6:7], s34, v81
	s_and_b64 vcc, vcc, s[6:7]
	v_add_u32_e32 v81, 0x91, v80
	s_movk_i32 s6, 0xff6e
	v_cndmask_b32_e32 v8, v246, v8, vcc
	v_cmp_lt_i32_e32 vcc, s6, v80
	v_cmp_gt_i32_e64 s[6:7], s34, v81
	s_and_b64 vcc, vcc, s[6:7]
	v_add_u32_e32 v81, 0x92, v80
	s_movk_i32 s6, 0xff6d
	v_cndmask_b32_e32 v9, v246, v9, vcc
	v_cmp_lt_i32_e32 vcc, s6, v80
	v_cmp_gt_i32_e64 s[6:7], s34, v81
	s_and_b64 vcc, vcc, s[6:7]
	v_add_u32_e32 v81, 0x93, v80
	s_movk_i32 s6, 0xff6c
	v_cndmask_b32_e32 v10, v246, v10, vcc
	v_cmp_lt_i32_e32 vcc, s6, v80
	v_cmp_gt_i32_e64 s[6:7], s34, v81
	s_and_b64 vcc, vcc, s[6:7]
	v_add_u32_e32 v81, 0x98, v80
	s_movk_i32 s6, 0xff67
	v_cndmask_b32_e32 v11, v246, v11, vcc
	v_cmp_lt_i32_e32 vcc, s6, v80
	v_cmp_gt_i32_e64 s[6:7], s34, v81
	s_and_b64 vcc, vcc, s[6:7]
	v_add_u32_e32 v81, 0x99, v80
	s_movk_i32 s6, 0xff66
	v_cndmask_b32_e32 v12, v246, v12, vcc
	v_cmp_lt_i32_e32 vcc, s6, v80
	v_cmp_gt_i32_e64 s[6:7], s34, v81
	s_and_b64 vcc, vcc, s[6:7]
	v_add_u32_e32 v81, 0x9a, v80
	s_movk_i32 s6, 0xff65
	v_cndmask_b32_e32 v13, v246, v13, vcc
	v_cmp_lt_i32_e32 vcc, s6, v80
	v_cmp_gt_i32_e64 s[6:7], s34, v81
	s_and_b64 vcc, vcc, s[6:7]
	v_add_u32_e32 v81, 0x9b, v80
	s_movk_i32 s6, 0xff64
	v_cndmask_b32_e32 v14, v246, v14, vcc
	v_cmp_lt_i32_e64 s[6:7], s6, v80
	v_cmp_gt_i32_e32 vcc, s34, v81
	s_and_b64 vcc, s[6:7], vcc
	s_nop 0
	v_cndmask_b32_e32 v15, v246, v15, vcc
	s_branch .LBB0_408

; __device__ __forceinline__ void at_task32(const Args& A, const At32& T, const At32& Tn, bf16x8 (&qf)[4], bf16x8 (&kf)[5][4], LAS unsigned char* lds, LAS unsigned char* vst, int lane) {
;     ...
;     float mx = -1e30f;
; #pragma unroll
;     for (int tile = 0; tile < 5; ++tile)
; #pragma unroll
;         for (int e = 0; e < 16; ++e) mx = fmaxf(mx, s[tile][e]);
;     { auto rr = __builtin_amdgcn_permlane32_swap(__float_as_uint(mx), __float_as_uint(mx), false, false); mx = fmaxf(__uint_as_float(rr[0]), __uint_as_float(rr[1])); }
;     float lsum = 0.f;
; #pragma unroll
;     for (int tile = 0; tile < 5; ++tile)
; #pragma unroll
;         for (int e = 0; e < 16; ++e) { const float p = __builtin_amdgcn_exp2f(s[tile][e] - mx); s[tile][e] = p; lsum += p; }
;     { auto rr = __builtin_amdgcn_permlane32_swap(__float_as_uint(lsum), __float_as_uint(lsum), false, false); lsum = __uint_as_float(rr[0]) + __uint_as_float(rr[1]); }
.LBB0_408:
	s_mov_b32 s6, 0xf149f2ca
	v_max3_f32 v80, v78, s6, v79
	v_max3_f32 v80, v80, v76, v77
	v_max3_f32 v80, v80, v74, v75
	v_max3_f32 v80, v80, v72, v73
	v_max3_f32 v80, v80, v70, v71
	v_max3_f32 v80, v80, v68, v69
	v_max3_f32 v80, v80, v66, v67
	v_max3_f32 v80, v80, v64, v65
	v_max3_f32 v80, v80, v48, v49
	v_max3_f32 v80, v80, v50, v51
	v_max3_f32 v80, v80, v52, v53
	v_max3_f32 v80, v80, v54, v55
	v_max3_f32 v80, v80, v56, v57
	v_max3_f32 v80, v80, v58, v59
	v_max3_f32 v80, v80, v60, v61
	v_max3_f32 v80, v80, v62, v63
	v_max3_f32 v80, v80, v32, v33
	v_max3_f32 v80, v80, v34, v35
	v_max3_f32 v80, v80, v36, v37
	v_max3_f32 v80, v80, v38, v39
	v_max3_f32 v80, v80, v40, v41
	v_max3_f32 v80, v80, v42, v43
	v_max3_f32 v80, v80, v44, v45
	v_max3_f32 v80, v80, v46, v47
	v_max3_f32 v80, v80, v16, v17
	v_max3_f32 v80, v80, v18, v19
	v_max3_f32 v80, v80, v20, v21
	v_max3_f32 v80, v80, v22, v23
	v_max3_f32 v80, v80, v24, v25
	v_max3_f32 v80, v80, v26, v27
	v_max3_f32 v80, v80, v28, v29
	v_max3_f32 v80, v80, v30, v31
	v_max3_f32 v80, v80, v0, v1
	v_max3_f32 v80, v80, v2, v3
	v_max3_f32 v80, v80, v4, v5
	v_max3_f32 v80, v80, v6, v7
	v_max3_f32 v80, v80, v8, v9
	v_max3_f32 v80, v80, v10, v11
	v_max3_f32 v80, v80, v12, v13
	v_max3_f32 v80, v80, v14, v15
	v_mov_b32_e32 v81, v80
	s_nop 1
	v_permlane32_swap_b32_e32 v80, v81
	v_max_f32_e32 v81, v81, v81
	v_max_f32_e32 v80, v80, v80
	v_max_f32_e32 v80, v80, v81
	v_sub_f32_e32 v78, v78, v80
	v_sub_f32_e32 v79, v79, v80
	v_sub_f32_e32 v121, v0, v80
	v_exp_f32_e32 v0, v78
	v_sub_f32_e32 v76, v76, v80
	v_sub_f32_e32 v122, v1, v80
	v_exp_f32_e32 v1, v79
	v_sub_f32_e32 v77, v77, v80
	v_sub_f32_e32 v123, v2, v80
	v_exp_f32_e32 v2, v76
	v_sub_f32_e32 v124, v3, v80
	v_exp_f32_e32 v3, v77
	v_sub_f32_e32 v125, v4, v80
	v_add_f32_e32 v4, 0, v0
	v_add_f32_e32 v4, v1, v4
	v_sub_f32_e32 v74, v74, v80
	v_add_f32_e32 v4, v2, v4
	v_sub_f32_e32 v75, v75, v80
	v_sub_f32_e32 v113, v19, v80
	v_add_f32_e32 v19, v3, v4
	v_exp_f32_e32 v4, v74
	v_sub_f32_e32 v72, v72, v80
	v_sub_f32_e32 v110, v16, v80
	v_exp_f32_e32 v16, v75
	v_sub_f32_e32 v73, v73, v80
	v_sub_f32_e32 v111, v17, v80
	v_exp_f32_e32 v17, v72
	v_sub_f32_e32 v112, v18, v80
	v_exp_f32_e32 v18, v73
	v_add_f32_e32 v19, v4, v19
	v_add_f32_e32 v19, v16, v19
	v_sub_f32_e32 v70, v70, v80
	v_add_f32_e32 v19, v17, v19
	v_sub_f32_e32 v71, v71, v80
	v_sub_f32_e32 v117, v23, v80
	v_add_f32_e32 v23, v18, v19
	v_exp_f32_e32 v19, v70
	v_sub_f32_e32 v68, v68, v80
	v_sub_f32_e32 v114, v20, v80
	v_exp_f32_e32 v20, v71
	v_sub_f32_e32 v69, v69, v80
	v_sub_f32_e32 v115, v21, v80
	v_exp_f32_e32 v21, v68
	v_sub_f32_e32 v116, v22, v80
	v_exp_f32_e32 v22, v69
	v_add_f32_e32 v23, v19, v23
	v_add_f32_e32 v23, v20, v23
	v_sub_f32_e32 v66, v66, v80
	v_add_f32_e32 v23, v21, v23
	v_sub_f32_e32 v67, v67, v80
	v_add_f32_e32 v68, v22, v23
	v_exp_f32_e32 v23, v66
	v_sub_f32_e32 v64, v64, v80
	v_sub_f32_e32 v118, v24, v80
	v_exp_f32_e32 v24, v67
	v_sub_f32_e32 v65, v65, v80
	v_sub_f32_e32 v119, v25, v80
	v_exp_f32_e32 v25, v64
	v_sub_f32_e32 v48, v48, v80
	v_sub_f32_e32 v120, v26, v80
	v_exp_f32_e32 v26, v65
	v_sub_f32_e32 v49, v49, v80
	v_add_f32_e32 v64, v23, v68
	v_exp_f32_e32 v94, v48
	v_sub_f32_e32 v50, v50, v80
	v_add_f32_e32 v64, v24, v64
	v_exp_f32_e32 v95, v49
	v_sub_f32_e32 v51, v51, v80
	v_add_f32_e32 v64, v25, v64
	v_exp_f32_e32 v96, v50
	v_sub_f32_e32 v52, v52, v80
	v_add_f32_e32 v64, v26, v64
	v_exp_f32_e32 v97, v51
	v_sub_f32_e32 v53, v53, v80
	v_add_f32_e32 v48, v94, v64
	v_exp_f32_e32 v98, v52
	v_sub_f32_e32 v54, v54, v80
	v_add_f32_e32 v48, v95, v48
	v_exp_f32_e32 v99, v53
	v_sub_f32_e32 v55, v55, v80
	v_add_f32_e32 v48, v96, v48
	v_exp_f32_e32 v100, v54
	v_sub_f32_e32 v56, v56, v80
	v_add_f32_e32 v48, v97, v48
	v_exp_f32_e32 v101, v55
	v_sub_f32_e32 v57, v57, v80
	v_add_f32_e32 v48, v98, v48
	v_exp_f32_e32 v102, v56
	v_sub_f32_e32 v58, v58, v80
	v_add_f32_e32 v48, v99, v48
	v_exp_f32_e32 v103, v57
	v_sub_f32_e32 v59, v59, v80
	v_add_f32_e32 v48, v100, v48
	v_exp_f32_e32 v104, v58
	v_sub_f32_e32 v60, v60, v80
	v_add_f32_e32 v48, v101, v48
	v_exp_f32_e32 v105, v59
	v_sub_f32_e32 v61, v61, v80
	v_add_f32_e32 v48, v102, v48
	v_exp_f32_e32 v106, v60
	v_sub_f32_e32 v62, v62, v80
	v_add_f32_e32 v48, v103, v48
	v_exp_f32_e32 v107, v61
	v_sub_f32_e32 v63, v63, v80
	v_add_f32_e32 v48, v104, v48
	v_exp_f32_e32 v108, v62
	v_sub_f32_e32 v32, v32, v80
	v_add_f32_e32 v48, v105, v48
	v_exp_f32_e32 v109, v63
	v_sub_f32_e32 v33, v33, v80
	v_add_f32_e32 v48, v106, v48
	v_exp_f32_e32 v77, v32
	v_sub_f32_e32 v34, v34, v80
	v_add_f32_e32 v48, v107, v48
	v_exp_f32_e32 v78, v33
	v_sub_f32_e32 v35, v35, v80
	v_add_f32_e32 v48, v108, v48
	v_exp_f32_e32 v79, v34
	v_sub_f32_e32 v36, v36, v80
	v_add_f32_e32 v48, v109, v48
	v_exp_f32_e32 v81, v35
	v_sub_f32_e32 v37, v37, v80
	v_add_f32_e32 v32, v77, v48
	v_exp_f32_e32 v82, v36
	v_sub_f32_e32 v38, v38, v80
	v_add_f32_e32 v32, v78, v32
	v_exp_f32_e32 v83, v37
	v_sub_f32_e32 v39, v39, v80
	v_add_f32_e32 v32, v79, v32
	v_exp_f32_e32 v84, v38
	v_sub_f32_e32 v40, v40, v80
	v_add_f32_e32 v32, v81, v32
	v_exp_f32_e32 v85, v39
	v_sub_f32_e32 v41, v41, v80
	v_add_f32_e32 v32, v82, v32
	v_exp_f32_e32 v86, v40
	v_sub_f32_e32 v42, v42, v80
	v_add_f32_e32 v32, v83, v32
	v_exp_f32_e32 v87, v41
	v_sub_f32_e32 v43, v43, v80
	v_add_f32_e32 v32, v84, v32
	v_exp_f32_e32 v88, v42
	v_sub_f32_e32 v44, v44, v80
	v_add_f32_e32 v32, v85, v32
	v_exp_f32_e32 v89, v43
	v_sub_f32_e32 v45, v45, v80
	v_add_f32_e32 v32, v86, v32
	v_exp_f32_e32 v90, v44
	v_sub_f32_e32 v46, v46, v80
	v_add_f32_e32 v32, v87, v32
	v_exp_f32_e32 v91, v45
	v_sub_f32_e32 v47, v47, v80
	v_add_f32_e32 v32, v88, v32
; #define LAS __attribute__((address_space(3)))
; __device__ __forceinline__ void at_task32(const Args& A, const At32& T, const At32& Tn, bf16x8 (&qf)[4], bf16x8 (&kf)[5][4], LAS unsigned char* lds, LAS unsigned char* vst, int lane) {
;     ...
;     for (int tile = 0; tile < 5; ++tile)
; #pragma unroll
;         for (int e = 0; e < 16; ++e) { const float p = __builtin_amdgcn_exp2f(s[tile][e] - mx); s[tile][e] = p; lsum += p; }
;     { auto rr = __builtin_amdgcn_permlane32_swap(__float_as_uint(lsum), __float_as_uint(lsum), false, false); lsum = __uint_as_float(rr[0]) + __uint_as_float(rr[1]); }
;     __builtin_amdgcn_sched_barrier(0);
;     u32x4 vr[8];
; #pragma unroll
;     for (int idx = 0; idx < 8; ++idx) { const int row = 8 * idx + (lane >> 3); int lk = lk0 + row; lk = lk < 0 ? 0 : (lk > L - 1 ? L - 1 : lk);
;         vr[idx] = *(const u32x4*)(Vb + ((unsigned)((lk << dsh) + r) * 2048u + 16u * (lane & 7))); }
;     f32x16 o[2];
; #pragma unroll
;     for (int db = 0; db < 2; ++db)
; #pragma unroll
;         for (int e = 0; e < 16; ++e) o[db][e] = 0.f;
;     const int i16 = lane & 15;
;     const LAS unsigned char* trb = vst + (4 * h + (i16 >> 2)) * VS_STRIDE + (((lane >> 4) & 1) * 16 + 4 * (i16 & 3)) * 2;
; #pragma unroll
;     for (int tile = 0; tile < 5; ++tile) {
; #pragma unroll
;         for (int it = 0; it < 4; ++it) { const int idx = it * 64 + lane, row = idx >> 3, ch = idx & 7; *(LAS u32x4*)(vst + row * VS_STRIDE + ch * 16) = vr[(tile & 1) * 4 + it]; }
;         if (tile < 3) {
; #pragma unroll
;             for (int it = 0; it < 4; ++it) { const int row = 32 * (tile + 2) + 8 * it + (lane >> 3); int lk = lk0 + row; lk = lk < 0 ? 0 : (lk > L - 1 ? L - 1 : lk);
;                 vr[(tile & 1) * 4 + it] = *(const u32x4*)(Vb + ((unsigned)((lk << dsh) + r) * 2048u + 16u * (lane & 7))); }
;         }
;         bf16x8 pf[2];
; #pragma unroll
;         for (int ks = 0; ks < 2; ++ks) { u32x4 pw; pw.x = cvt_pk_bf16(s[tile][8 * ks + 0], s[tile][8 * ks + 1]); pw.y = cvt_pk_bf16(s[tile][8 * ks + 2], s[tile][8 * ks + 3]);
;             pw.z = cvt_pk_bf16(s[tile][8 * ks + 4], s[tile][8 * ks + 5]); pw.w = cvt_pk_bf16(s[tile][8 * ks + 6], s[tile][8 * ks + 7]); pf[ks] = __builtin_bit_cast(bf16x8, pw); }
;         asm volatile("s_waitcnt lgkmcnt(0)" ::: "memory");
; #pragma unroll
;         for (int ks = 0; ks < 2; ++ks)
; #pragma unroll
	v_exp_f32_e32 v92, v46
	v_add_f32_e32 v32, v89, v32
	v_exp_f32_e32 v93, v47
	v_add_f32_e32 v32, v90, v32
	v_exp_f32_e32 v61, v110
	v_add_f32_e32 v32, v91, v32
	v_exp_f32_e32 v62, v111
	v_add_f32_e32 v32, v92, v32
	v_exp_f32_e32 v63, v112
	v_add_f32_e32 v32, v93, v32
	v_exp_f32_e32 v64, v113
	v_add_f32_e32 v32, v61, v32
	v_exp_f32_e32 v65, v114
	v_add_f32_e32 v32, v62, v32
	v_exp_f32_e32 v66, v115
	v_add_f32_e32 v32, v63, v32
	v_exp_f32_e32 v67, v116
	v_add_f32_e32 v32, v64, v32
	v_exp_f32_e32 v68, v117
	v_add_f32_e32 v32, v65, v32
	v_exp_f32_e32 v69, v118
	v_add_f32_e32 v32, v66, v32
	v_exp_f32_e32 v70, v119
	v_sub_f32_e32 v27, v27, v80
	v_add_f32_e32 v32, v67, v32
	v_exp_f32_e32 v71, v120
	v_sub_f32_e32 v28, v28, v80
	v_add_f32_e32 v32, v68, v32
	v_exp_f32_e32 v72, v27
	v_sub_f32_e32 v29, v29, v80
	v_add_f32_e32 v27, v69, v32
	v_exp_f32_e32 v73, v28
	v_sub_f32_e32 v30, v30, v80
	v_add_f32_e32 v27, v70, v27
	v_exp_f32_e32 v74, v29
	v_sub_f32_e32 v31, v31, v80
	v_add_f32_e32 v27, v71, v27
	v_exp_f32_e32 v75, v30
	v_add_f32_e32 v27, v72, v27
	v_exp_f32_e32 v76, v31
	v_add_f32_e32 v27, v73, v27
	v_exp_f32_e32 v56, v121
	v_add_f32_e32 v27, v74, v27
	v_exp_f32_e32 v57, v122
	v_add_f32_e32 v27, v75, v27
	v_exp_f32_e32 v58, v123
	v_add_f32_e32 v27, v76, v27
	v_exp_f32_e32 v59, v124
	v_add_f32_e32 v27, v56, v27
	v_exp_f32_e32 v60, v125
	v_sub_f32_e32 v5, v5, v80
	v_add_f32_e32 v27, v57, v27
	v_exp_f32_e32 v112, v5
	v_sub_f32_e32 v5, v6, v80
	v_add_f32_e32 v27, v58, v27
	v_exp_f32_e32 v113, v5
	v_sub_f32_e32 v5, v7, v80
	v_add_f32_e32 v27, v59, v27
	v_exp_f32_e32 v114, v5
	v_sub_f32_e32 v6, v8, v80
	v_add_f32_e32 v5, v60, v27
	v_exp_f32_e32 v115, v6
	v_sub_f32_e32 v6, v9, v80
	v_add_f32_e32 v5, v112, v5
	v_exp_f32_e32 v116, v6
	v_sub_f32_e32 v6, v10, v80
	v_add_f32_e32 v5, v113, v5
	v_exp_f32_e32 v117, v6
	v_sub_f32_e32 v6, v11, v80
	v_add_f32_e32 v5, v114, v5
	v_exp_f32_e32 v118, v6
	v_sub_f32_e32 v6, v12, v80
	v_add_f32_e32 v5, v115, v5
	v_exp_f32_e32 v119, v6
	v_sub_f32_e32 v6, v13, v80
	v_add_f32_e32 v5, v116, v5
	v_exp_f32_e32 v120, v6
	v_sub_f32_e32 v6, v14, v80
	v_add_f32_e32 v5, v117, v5
	v_exp_f32_e32 v121, v6
	v_sub_f32_e32 v6, v15, v80
	v_add_f32_e32 v5, v118, v5
	v_exp_f32_e32 v122, v6
	s_ashr_i32 s6, s22, 4
	v_add_f32_e32 v5, v119, v5
	s_ashr_i32 s7, s6, 31
	v_add_f32_e32 v5, v120, v5
	s_lshl_b32 s22, s22, 7
	s_lshl_b64 s[6:7], s[6:7], 24
	v_readlane_b32 vcc_lo, v253, 58
	v_add_f32_e32 v5, v121, v5
	s_add_u32 s6, vcc_lo, s6
	v_readlane_b32 vcc_lo, v253, 59
	v_add_f32_e32 v110, v122, v5
	s_addc_u32 s7, vcc_lo, s7
	s_and_b32 s22, s22, 0x780
	v_mov_b32_e32 v111, v110
	s_add_u32 s6, s6, s22
	s_nop 0
	v_permlane32_swap_b32_e32 v110, v111
	s_addc_u32 s7, s7, 0
	s_add_i32 s34, s34, -1
	s_movk_i32 s22, 0xffdf
	v_add_u32_e32 v123, s3, v172
	s_lshl_b32 s3, s28, 7
	s_and_b32 s3, s3, 0x780
	v_min_i32_e32 v5, s34, v123
	v_cmp_lt_i32_e32 vcc, -1, v123
	s_waitcnt vmcnt(4)
	ds_write_b128 v201, v[212:215]
	ds_write_b128 v201, v[216:219] offset:1280
	ds_write_b128 v201, v[220:223] offset:2560
	ds_write_b128 v201, v[224:227] offset:3840
	v_cndmask_b32_e32 v5, 0, v5, vcc
	v_lshlrev_b32_e32 v5, s27, v5
	v_add_u32_e32 v5, s31, v5
	v_lshl_or_b32 v5, v5, 11, v173
	global_load_dwordx4 v[48:51], v5, s[6:7]
	v_add_u32_e32 v5, 8, v123
	v_min_i32_e32 v5, s34, v5
	v_cmp_lt_i32_e32 vcc, -9, v123
	s_nop 1
	v_cndmask_b32_e32 v5, 0, v5, vcc
	v_lshlrev_b32_e32 v5, s27, v5
	v_add_u32_e32 v5, s31, v5
	v_lshl_or_b32 v5, v5, 11, v173
	global_load_dwordx4 v[52:55], v5, s[6:7]
	v_add_u32_e32 v5, 16, v123
	v_min_i32_e32 v5, s34, v5
	v_cmp_lt_i32_e32 vcc, s19, v123
	s_nop 1
	v_cndmask_b32_e32 v5, 0, v5, vcc
	v_lshlrev_b32_e32 v5, s27, v5
	v_add_u32_e32 v5, s31, v5
	v_lshl_or_b32 v5, v5, 11, v173
	global_load_dwordx4 v[124:127], v5, s[6:7]
	v_add_u32_e32 v5, 24, v123
	v_min_i32_e32 v5, s34, v5
	v_cmp_lt_i32_e32 vcc, s12, v123
	s_nop 1
	v_cndmask_b32_e32 v5, 0, v5, vcc
	v_lshlrev_b32_e32 v5, s27, v5
	v_add_u32_e32 v5, s31, v5
	v_lshl_or_b32 v5, v5, 11, v173
	global_load_dwordx4 v[128:131], v5, s[6:7]
	v_cvt_pk_bf16_f32 v0, v0, v1
	v_cvt_pk_bf16_f32 v1, v2, v3
	v_cvt_pk_bf16_f32 v2, v4, v16
	v_cvt_pk_bf16_f32 v3, v17, v18
	v_cvt_pk_bf16_f32 v132, v19, v20
	v_cvt_pk_bf16_f32 v133, v21, v22
	v_cvt_pk_bf16_f32 v134, v23, v24
	v_cvt_pk_bf16_f32 v135, v25, v26
	s_waitcnt lgkmcnt(0)
	ds_read_b64_tr_b16 v[4:5], v202
	ds_read_b64_tr_b16 v[6:7], v202 offset:1280
	s_waitcnt lgkmcnt(0)
	v_mfma_f32_32x32x16_bf16 v[16:31], v[4:7], v[0:3], 0
	ds_read_b64_tr_b16 v[4:5], v202 offset:64
	ds_read_b64_tr_b16 v[6:7], v202 offset:1344
	ds_read_b64_tr_b16 v[136:137], v202 offset:2560
	ds_read_b64_tr_b16 v[138:139], v202 offset:3840
	v_cmp_lt_i32_e32 vcc, s22, v123
	s_waitcnt lgkmcnt(0)
	v_mfma_f32_32x32x16_bf16 v[16:31], v[136:139], v[132:135], v[16:31]
	ds_read_b64_tr_b16 v[136:137], v202 offset:2624
	ds_read_b64_tr_b16 v[138:139], v202 offset:3904
	s_waitcnt lgkmcnt(0)
	s_waitcnt vmcnt(7)
	ds_write_b128 v201, v[228:231]
	s_waitcnt vmcnt(6)
	ds_write_b128 v201, v[232:235] offset:1280
	s_waitcnt vmcnt(5)
	ds_write_b128 v201, v[248:251] offset:2560
	s_waitcnt vmcnt(4)
	ds_write_b128 v201, v[236:239] offset:3840
	v_add_u32_e32 v32, 32, v123
	v_min_i32_e32 v32, s34, v32
	v_add_u32_e32 v36, 40, v123
	v_cndmask_b32_e32 v32, 0, v32, vcc
	v_min_i32_e32 v36, s34, v36
	v_cmp_lt_i32_e32 vcc, s29, v123
	v_add_u32_e32 v40, 48, v123
	v_min_i32_e32 v40, s34, v40
	v_cndmask_b32_e32 v36, 0, v36, vcc
	v_cmp_lt_i32_e32 vcc, s2, v123
	v_add_u32_e32 v44, 56, v123
	v_mfma_f32_32x32x16_bf16 v[0:15], v[4:7], v[0:3], 0
	v_cndmask_b32_e32 v40, 0, v40, vcc
	v_min_i32_e32 v44, s34, v44
	v_cmp_lt_i32_e32 vcc, s18, v123
	v_lshlrev_b32_e32 v32, s27, v32
	v_lshlrev_b32_e32 v36, s27, v36
	v_cndmask_b32_e32 v44, 0, v44, vcc
	v_lshlrev_b32_e32 v40, s27, v40
	v_lshlrev_b32_e32 v44, s27, v44
	v_add_u32_e32 v32, s31, v32
	v_add_u32_e32 v36, s31, v36
	v_add_u32_e32 v40, s31, v40
	v_add_u32_e32 v44, s31, v44
	v_lshl_or_b32 v32, v32, 11, v173
	v_lshl_or_b32 v36, v36, 11, v173
	v_lshl_or_b32 v40, v40, 11, v173
	v_lshl_or_b32 v44, v44, 11, v173
	global_load_dwordx4 v[32:35], v32, s[6:7]
	s_waitcnt lgkmcnt(4)
; __device__ __forceinline__ unsigned cvt_pk_bf16(float lo, float hi) { unsigned r; asm volatile("v_cvt_pk_bf16_f32 %0, %1, %2" : "=v"(r) : "v"(lo), "v"(hi)); return r; }
; #define LAS __attribute__((address_space(3)))
; __device__ __forceinline__ void at_task32(const Args& A, const At32& T, const At32& Tn, bf16x8 (&qf)[4], bf16x8 (&kf)[5][4], LAS unsigned char* lds, LAS unsigned char* vst, int lane) {
;     ...
;     for (int tile = 0; tile < 5; ++tile) {
; #pragma unroll
;         for (int it = 0; it < 4; ++it) { const int idx = it * 64 + lane, row = idx >> 3, ch = idx & 7; *(LAS u32x4*)(vst + row * VS_STRIDE + ch * 16) = vr[(tile & 1) * 4 + it]; }
;         if (tile < 3) {
; #pragma unroll
;             for (int it = 0; it < 4; ++it) { const int row = 32 * (tile + 2) + 8 * it + (lane >> 3); int lk = lk0 + row; lk = lk < 0 ? 0 : (lk > L - 1 ? L - 1 : lk);
;                 vr[(tile & 1) * 4 + it] = *(const u32x4*)(Vb + ((unsigned)((lk << dsh) + r) * 2048u + 16u * (lane & 7))); }
;         }
;         bf16x8 pf[2];
; #pragma unroll
;         for (int ks = 0; ks < 2; ++ks) { u32x4 pw; pw.x = cvt_pk_bf16(s[tile][8 * ks + 0], s[tile][8 * ks + 1]); pw.y = cvt_pk_bf16(s[tile][8 * ks + 2], s[tile][8 * ks + 3]);
;             pw.z = cvt_pk_bf16(s[tile][8 * ks + 4], s[tile][8 * ks + 5]); pw.w = cvt_pk_bf16(s[tile][8 * ks + 6], s[tile][8 * ks + 7]); pf[ks] = __builtin_bit_cast(bf16x8, pw); }
;         asm volatile("s_waitcnt lgkmcnt(0)" ::: "memory");
; #pragma unroll
;         for (int ks = 0; ks < 2; ++ks)
; #pragma unroll
;             for (int db = 0; db < 2; ++db) { const bf16x8 af = tr_pair(trb + (16 * ks) * VS_STRIDE + db * 64, trb + (16 * ks + 8) * VS_STRIDE + db * 64);
;                 o[db] = __builtin_amdgcn_mfma_f32_32x32x16_bf16(af, pf[ks], o[db], 0, 0, 0); }
;         asm volatile("s_waitcnt lgkmcnt(0)" ::: "memory");
;     }
	v_mfma_f32_32x32x16_bf16 v[0:15], v[136:139], v[132:135], v[0:15]
	global_load_dwordx4 v[36:39], v36, s[6:7]
	s_movk_i32 s18, 0xffbf
	global_load_dwordx4 v[40:43], v40, s[6:7]
	v_cmp_lt_i32_e32 vcc, s18, v123
	global_load_dwordx4 v[44:47], v44, s[6:7]
	v_cvt_pk_bf16_f32 v94, v94, v95
	v_cvt_pk_bf16_f32 v95, v96, v97
	v_cvt_pk_bf16_f32 v96, v98, v99
	v_cvt_pk_bf16_f32 v97, v100, v101
	v_cvt_pk_bf16_f32 v98, v102, v103
	v_cvt_pk_bf16_f32 v99, v104, v105
	v_cvt_pk_bf16_f32 v100, v106, v107
	v_cvt_pk_bf16_f32 v101, v108, v109
	s_waitcnt lgkmcnt(0)
	ds_read_b64_tr_b16 v[102:103], v202
	ds_read_b64_tr_b16 v[104:105], v202 offset:1280
	s_waitcnt lgkmcnt(0)
	v_mfma_f32_32x32x16_bf16 v[16:31], v[102:105], v[94:97], v[16:31]
	ds_read_b64_tr_b16 v[102:103], v202 offset:64
	ds_read_b64_tr_b16 v[104:105], v202 offset:1344
	s_movk_i32 s2, 0xffdf
	s_waitcnt lgkmcnt(0)
	v_mfma_f32_32x32x16_bf16 v[0:15], v[102:105], v[94:97], v[0:15]
	ds_read_b64_tr_b16 v[94:95], v202 offset:2560
	ds_read_b64_tr_b16 v[96:97], v202 offset:3840
	s_waitcnt lgkmcnt(0)
	v_mfma_f32_32x32x16_bf16 v[16:31], v[94:97], v[98:101], v[16:31]
	ds_read_b64_tr_b16 v[94:95], v202 offset:2624
	ds_read_b64_tr_b16 v[96:97], v202 offset:3904
	s_waitcnt lgkmcnt(0)
	s_waitcnt vmcnt(7)
	ds_write_b128 v201, v[48:51]
	s_waitcnt vmcnt(6)
	ds_write_b128 v201, v[52:55] offset:1280
	s_waitcnt vmcnt(5)
	ds_write_b128 v201, v[124:127] offset:2560
	s_waitcnt vmcnt(4)
	ds_write_b128 v201, v[128:131] offset:3840
	v_add_u32_e32 v48, 64, v123
	v_min_i32_e32 v48, s34, v48
	v_add_u32_e32 v52, 0x48, v123
	v_cndmask_b32_e32 v48, 0, v48, vcc
	s_waitcnt lgkmcnt(4)
	v_mfma_f32_32x32x16_bf16 v[0:15], v[94:97], v[98:101], v[0:15]
	v_min_i32_e32 v52, s34, v52
	v_cmp_lt_i32_e32 vcc, s20, v123
	v_add_u32_e32 v94, 0x50, v123
	v_lshlrev_b32_e32 v48, s27, v48
	v_cndmask_b32_e32 v52, 0, v52, vcc
	v_min_i32_e32 v94, s34, v94
	v_cmp_lt_i32_e32 vcc, s13, v123
	v_add_u32_e32 v98, 0x58, v123
	v_add_u32_e32 v48, s31, v48
	v_lshlrev_b32_e32 v52, s27, v52
	v_cndmask_b32_e32 v94, 0, v94, vcc
	v_min_i32_e32 v98, s34, v98
	v_cmp_lt_i32_e32 vcc, s15, v123
	v_lshl_or_b32 v48, v48, 11, v173
	v_add_u32_e32 v52, s31, v52
	v_lshlrev_b32_e32 v94, s27, v94
	v_cndmask_b32_e32 v98, 0, v98, vcc
	global_load_dwordx4 v[48:51], v48, s[6:7]
	v_lshl_or_b32 v52, v52, 11, v173
	v_add_u32_e32 v94, s31, v94
	v_lshlrev_b32_e32 v98, s27, v98
	global_load_dwordx4 v[52:55], v52, s[6:7]
	v_lshl_or_b32 v94, v94, 11, v173
	v_add_u32_e32 v98, s31, v98
	global_load_dwordx4 v[94:97], v94, s[6:7]
	v_lshl_or_b32 v98, v98, 11, v173
	global_load_dwordx4 v[98:101], v98, s[6:7]
	v_cvt_pk_bf16_f32 v102, v77, v78
	v_cvt_pk_bf16_f32 v103, v79, v81
	v_cvt_pk_bf16_f32 v104, v82, v83
	v_cvt_pk_bf16_f32 v105, v84, v85
	v_cvt_pk_bf16_f32 v82, v86, v87
	v_cvt_pk_bf16_f32 v83, v88, v89
	v_cvt_pk_bf16_f32 v84, v90, v91
	v_cvt_pk_bf16_f32 v85, v92, v93
	s_waitcnt lgkmcnt(0)
	ds_read_b64_tr_b16 v[86:87], v202
	ds_read_b64_tr_b16 v[88:89], v202 offset:1280
	s_waitcnt lgkmcnt(0)
	v_mfma_f32_32x32x16_bf16 v[16:31], v[86:89], v[102:105], v[16:31]
	ds_read_b64_tr_b16 v[86:87], v202 offset:64
	ds_read_b64_tr_b16 v[88:89], v202 offset:1344
	s_ashr_i32 s6, s28, 4
	s_ashr_i32 s7, s6, 31
	s_lshl_b64 s[6:7], s[6:7], 24
	s_or_b32 s3, s6, s3
	v_readlane_b32 s12, v253, 49
	v_readlane_b32 s13, v253, 50
	s_waitcnt lgkmcnt(0)
	v_mfma_f32_32x32x16_bf16 v[0:15], v[86:89], v[102:105], v[0:15]
	ds_read_b64_tr_b16 v[86:87], v202 offset:2560
	ds_read_b64_tr_b16 v[88:89], v202 offset:3840
	s_add_u32 s34, s12, s3
	s_addc_u32 s35, s13, s7
	s_lshr_b32 s22, 0x2000, s23
	v_add_f32_e32 v81, v110, v111
	s_movk_i32 s13, 0xffdf
	s_waitcnt lgkmcnt(0)
	v_mfma_f32_32x32x16_bf16 v[16:31], v[86:89], v[82:85], v[16:31]
	ds_read_b64_tr_b16 v[86:87], v202 offset:2624
	ds_read_b64_tr_b16 v[88:89], v202 offset:3904
	s_waitcnt lgkmcnt(0)
	s_waitcnt vmcnt(7)
	ds_write_b128 v201, v[32:35]
	s_waitcnt vmcnt(6)
	ds_write_b128 v201, v[36:39] offset:1280
	s_waitcnt vmcnt(5)
	ds_write_b128 v201, v[40:43] offset:2560
	s_waitcnt vmcnt(4)
	ds_write_b128 v201, v[44:47] offset:3840
	v_cvt_pk_bf16_f32 v32, v61, v62
	v_cvt_pk_bf16_f32 v33, v63, v64
	v_cvt_pk_bf16_f32 v34, v65, v66
	v_cvt_pk_bf16_f32 v35, v67, v68
	v_cvt_pk_bf16_f32 v36, v69, v70
	v_cvt_pk_bf16_f32 v37, v71, v72
	v_cvt_pk_bf16_f32 v38, v73, v74
	v_cvt_pk_bf16_f32 v39, v75, v76
	s_waitcnt lgkmcnt(0)
	ds_read_b64_tr_b16 v[40:41], v202
	ds_read_b64_tr_b16 v[42:43], v202 offset:1280
	s_waitcnt lgkmcnt(6)
	v_mfma_f32_32x32x16_bf16 v[0:15], v[86:89], v[82:85], v[0:15]
	s_waitcnt lgkmcnt(0)
	v_mfma_f32_32x32x16_bf16 v[16:31], v[40:43], v[32:35], v[16:31]
	ds_read_b64_tr_b16 v[40:41], v202 offset:64
	ds_read_b64_tr_b16 v[42:43], v202 offset:1344
	s_waitcnt lgkmcnt(0)
	v_mfma_f32_32x32x16_bf16 v[0:15], v[40:43], v[32:35], v[0:15]
	ds_read_b64_tr_b16 v[32:33], v202 offset:2560
	ds_read_b64_tr_b16 v[34:35], v202 offset:3840
	s_waitcnt lgkmcnt(0)
; #define LAS __attribute__((address_space(3)))
; __device__ __forceinline__ void at32_load_qk(const Args& A, const At32& T, int lane, bf16x8 (&qf)[4], bf16x8 (&kf)[5][4]) {
;     const int L = SEQ >> T.dsh, q32 = lane & 31, h = lane >> 5, lk0 = T.lq0 - 64;
;     const size_t hb = ((size_t)(T.bh >> 4) * SEQ * 1024 + (T.bh & 15) * 64) * 2;
;     const char* Qb = (const char*)(A.ws + WS_Q) + hb; const char* Kb = (const char*)(A.ws + WS_K) + hb;
;     const unsigned qo = (unsigned)(((T.lq0 + q32) << T.dsh) + T.r) * 2048u + 16u * h;
; #pragma unroll
;     for (int ds = 0; ds < 4; ++ds) qf[ds] = *(const bf16x8*)(Qb + qo + 32 * ds);
; #pragma unroll
;     for (int tile = 0; tile < 5; ++tile) { int lk = lk0 + 32 * tile + q32; lk = lk < 0 ? 0 : (lk > L - 1 ? L - 1 : lk);
;         const unsigned ko = (unsigned)((lk << T.dsh) + T.r) * 2048u + 16u * h;
; #pragma unroll
;         for (int ds = 0; ds < 4; ++ds) kf[tile][ds] = *(const bf16x8*)(Kb + ko + 32 * ds); }
; __device__ __forceinline__ void at_task32(const Args& A, const At32& T, const At32& Tn, bf16x8 (&qf)[4], bf16x8 (&kf)[5][4], LAS unsigned char* lds, LAS unsigned char* vst, int lane) {
;     ...
;         for (int ks = 0; ks < 2; ++ks)
; #pragma unroll
;             for (int db = 0; db < 2; ++db) { const bf16x8 af = tr_pair(trb + (16 * ks) * VS_STRIDE + db * 64, trb + (16 * ks + 8) * VS_STRIDE + db * 64);
;                 o[db] = __builtin_amdgcn_mfma_f32_32x32x16_bf16(af, pf[ks], o[db], 0, 0, 0); }
;         asm volatile("s_waitcnt lgkmcnt(0)" ::: "memory");
;     }
;     asm volatile("" ::: "memory");
;     at32_load_qk(A, Tn, lane, qf, kf);
;     asm volatile("" ::: "memory");
;     const int ql = qoff + (q32 << dsh);
;     LAS unsigned char* orow = lds + ql * OB_STRIDE + 8 * h;
;     float ca = 0.f, cbb = 1.f, mn = mx, ln = lsum;
;     if (mode != 0) { const f32x2 ml = *(const LAS f32x2*)(ML + 2 * ql); mn = fmaxf(ml[0], mx); ca = __builtin_amdgcn_exp2f(ml[0] - mn); cbb = __builtin_amdgcn_exp2f(mx - mn); ln = ca * ml[1] + cbb * lsum; }
	v_mfma_f32_32x32x16_bf16 v[16:31], v[32:35], v[36:39], v[16:31]
	ds_read_b64_tr_b16 v[32:33], v202 offset:2624
	ds_read_b64_tr_b16 v[34:35], v202 offset:3904
	s_waitcnt lgkmcnt(0)
	s_waitcnt vmcnt(3)
	ds_write_b128 v201, v[48:51]
	s_waitcnt vmcnt(2)
	ds_write_b128 v201, v[52:55] offset:1280
	s_waitcnt vmcnt(1)
	ds_write_b128 v201, v[94:97] offset:2560
	s_waitcnt vmcnt(0)
	ds_write_b128 v201, v[98:101] offset:3840
	s_waitcnt lgkmcnt(4)
	v_mfma_f32_32x32x16_bf16 v[0:15], v[32:35], v[36:39], v[0:15]
	v_cvt_pk_bf16_f32 v32, v56, v57
	v_cvt_pk_bf16_f32 v33, v58, v59
	v_cvt_pk_bf16_f32 v34, v60, v112
	v_cvt_pk_bf16_f32 v35, v113, v114
	v_cvt_pk_bf16_f32 v36, v115, v116
	v_cvt_pk_bf16_f32 v37, v117, v118
	v_cvt_pk_bf16_f32 v38, v119, v120
	v_cvt_pk_bf16_f32 v39, v121, v122
	s_waitcnt lgkmcnt(0)
	ds_read_b64_tr_b16 v[40:41], v202
	ds_read_b64_tr_b16 v[42:43], v202 offset:1280
	s_waitcnt lgkmcnt(0)
	v_mfma_f32_32x32x16_bf16 v[16:31], v[40:43], v[32:35], v[16:31]
	ds_read_b64_tr_b16 v[40:41], v202 offset:64
	ds_read_b64_tr_b16 v[42:43], v202 offset:1344
	v_add_u32_e32 v52, s17, v169
	v_cmp_lt_i32_e32 vcc, 63, v52
	v_subrev_u32_e32 v48, 32, v52
	s_waitcnt lgkmcnt(0)
	v_mfma_f32_32x32x16_bf16 v[0:15], v[40:43], v[32:35], v[0:15]
	ds_read_b64_tr_b16 v[32:33], v202 offset:2560
	ds_read_b64_tr_b16 v[34:35], v202 offset:3840
	s_waitcnt lgkmcnt(0)
	v_mfma_f32_32x32x16_bf16 v[16:31], v[32:35], v[36:39], v[16:31]
	ds_read_b64_tr_b16 v[32:33], v202 offset:2624
	ds_read_b64_tr_b16 v[34:35], v202 offset:3904
	s_waitcnt lgkmcnt(0)
	s_waitcnt lgkmcnt(0)
	v_mfma_f32_32x32x16_bf16 v[0:15], v[32:35], v[36:39], v[0:15]
	v_lshlrev_b32_e32 v32, s23, v52
	v_add_u32_e32 v32, s16, v32
	v_lshl_or_b32 v32, v32, 11, v170
	global_load_dwordx4 v[68:71], v32, s[34:35]
	global_load_dwordx4 v[72:75], v32, s[34:35] offset:32
	global_load_dwordx4 v[94:97], v32, s[34:35] offset:64
	global_load_dwordx4 v[64:67], v32, s[34:35] offset:96
	v_readlane_b32 s34, v253, 53
	v_readlane_b32 s35, v253, 54
	s_add_u32 s6, s34, s3
	s_addc_u32 s7, s35, s7
	v_subrev_u32_e32 v32, 64, v52
	s_add_i32 s22, s22, -1
	v_min_i32_e32 v32, s22, v32
	v_cndmask_b32_e32 v32, 0, v32, vcc
	v_min_i32_e32 v48, s22, v48
	v_cmp_lt_i32_e32 vcc, 31, v52
	v_lshlrev_b32_e32 v32, s23, v32
	v_add_u32_e32 v32, s16, v32
	v_cndmask_b32_e32 v48, 0, v48, vcc
	v_lshlrev_b32_e32 v48, s23, v48
	v_add_u32_e32 v48, s16, v48
	v_lshl_or_b32 v44, v32, 11, v170
	v_lshl_or_b32 v53, v48, 11, v170
	global_load_dwordx4 v[32:35], v44, s[6:7]
	global_load_dwordx4 v[36:39], v44, s[6:7] offset:32
	global_load_dwordx4 v[40:43], v44, s[6:7] offset:64
	s_nop 0
	global_load_dwordx4 v[44:47], v44, s[6:7] offset:96
	s_nop 0
	global_load_dwordx4 v[48:51], v53, s[6:7]
	global_load_dwordx4 v[98:101], v53, s[6:7] offset:32
	global_load_dwordx4 v[102:105], v53, s[6:7] offset:64
	global_load_dwordx4 v[106:109], v53, s[6:7] offset:96
	v_min_i32_e32 v53, s22, v52
	v_cmp_lt_i32_e32 vcc, -1, v52
	s_cmp_lg_u32 s11, 0
	s_cselect_b64 s[34:35], -1, 0
	v_cndmask_b32_e32 v53, 0, v53, vcc
	v_lshlrev_b32_e32 v53, s23, v53
	v_add_u32_e32 v53, s16, v53
	v_lshl_or_b32 v53, v53, 11, v170
	global_load_dwordx4 v[114:117], v53, s[6:7]
	global_load_dwordx4 v[118:121], v53, s[6:7] offset:32
	global_load_dwordx4 v[122:125], v53, s[6:7] offset:64
	global_load_dwordx4 v[110:113], v53, s[6:7] offset:96
	v_add_u32_e32 v53, 32, v52
	v_min_i32_e32 v53, s22, v53
	v_cmp_lt_i32_e32 vcc, s2, v52
	s_cmp_eq_u32 s11, 0
	s_nop 0
	v_cndmask_b32_e32 v53, 0, v53, vcc
	v_lshlrev_b32_e32 v53, s23, v53
	v_add_u32_e32 v53, s16, v53
	v_lshl_or_b32 v53, v53, 11, v170
	global_load_dwordx4 v[126:129], v53, s[6:7]
	global_load_dwordx4 v[130:133], v53, s[6:7] offset:32
	global_load_dwordx4 v[134:137], v53, s[6:7] offset:64
	global_load_dwordx4 v[138:141], v53, s[6:7] offset:96
	v_add_u32_e32 v53, 64, v52
	v_min_i32_e32 v53, s22, v53
	v_cmp_lt_i32_e32 vcc, s18, v52
	s_nop 1
	v_cndmask_b32_e32 v52, 0, v53, vcc
	v_lshlrev_b32_e32 v52, s23, v52
	v_add_u32_e32 v52, s16, v52
	v_lshl_or_b32 v52, v52, 11, v170
	global_load_dwordx4 v[146:149], v52, s[6:7]
	global_load_dwordx4 v[150:153], v52, s[6:7] offset:32
	global_load_dwordx4 v[154:157], v52, s[6:7] offset:64
	global_load_dwordx4 v[142:145], v52, s[6:7] offset:96
	v_lshlrev_b32_e32 v52, s27, v169
	v_add_u32_e32 v54, s33, v52
	v_lshl_add_u32 v62, v54, 3, 0
	s_cbranch_scc1 .LBB0_388
	v_add_u32_e32 v52, 0x12000, v62
	ds_read_b64 v[52:53], v52
	v_max_f32_e32 v55, v80, v80
	s_waitcnt lgkmcnt(0)
	v_max_f32_e32 v56, v52, v52
	v_max_f32_e32 v55, v56, v55
	v_sub_f32_e32 v52, v52, v55
	v_sub_f32_e32 v57, v80, v55
	v_exp_f32_e32 v56, v52
	v_exp_f32_e32 v57, v57
	v_mov_b32_e32 v80, v53
	v_mov_b32_e32 v53, v56
	v_pk_mul_f32 v[58:59], v[80:81], v[56:57]
	v_mov_b32_e32 v52, v57
	v_add_f32_e32 v81, v58, v59
	v_mov_b32_e32 v80, v55
	s_cmp_lg_u32 s11, 2
	s_cbranch_scc1 .LBB0_411

; #define PHASE_END   if (A.coop && ph + 1 < A.ph_hi) { if (A.pad == 0x7fffffff) cg::this_grid().sync();   xcd_barrier(bar); } } ++ph;
; __global__ void __launch_bounds__(NTHR, 2) mega_fwd(Args A) {
;     ...
;         if (!even) { if (wave >= 4) __builtin_amdgcn_s_setprio(1);     attn_phase(A, lds, tid, lane, wave, bx, G); __builtin_amdgcn_s_setprio(0); }
;     ...
;         REP_END
;         PHASE_END
.LBB0_431:
	v_readlane_b32 s67, v254, 48
	v_readlane_b32 s5, v254, 56
	v_mov_b32_e32 v238, 1

; #define LAS __attribute__((address_space(3)))
; __global__ void __launch_bounds__(NTHR, 2) mega_fwd(Args A) {
;     extern __shared__ __attribute__((aligned(16))) unsigned char lds_raw[];
;     LAS unsigned char* lds = (LAS unsigned char*)lds_raw;
	.amdhsa_kernel _Z8mega_fwd4Args
		.amdhsa_group_segment_fixed_size 0
		.amdhsa_private_segment_fixed_size 0
		.amdhsa_kernarg_size 440
		.amdhsa_user_sgpr_count 2
		.amdhsa_user_sgpr_dispatch_ptr 0
		.amdhsa_user_sgpr_queue_ptr 0
		.amdhsa_user_sgpr_kernarg_segment_ptr 1
		.amdhsa_user_sgpr_dispatch_id 0
		.amdhsa_user_sgpr_kernarg_preload_length 0
		.amdhsa_user_sgpr_kernarg_preload_offset 0
		.amdhsa_user_sgpr_private_segment_size 0
		.amdhsa_uses_dynamic_stack 0
		.amdhsa_enable_private_segment 0
		.amdhsa_system_sgpr_workgroup_id_x 1
		.amdhsa_system_sgpr_workgroup_id_y 0
		.amdhsa_system_sgpr_workgroup_id_z 0
		.amdhsa_system_sgpr_workgroup_info 0
		.amdhsa_system_vgpr_workitem_id 2
		.amdhsa_next_free_vgpr 256
		.amdhsa_next_free_sgpr 102
		.amdhsa_accum_offset 256
		.amdhsa_reserve_vcc 1
		.amdhsa_float_round_mode_32 0
		.amdhsa_float_round_mode_16_64 0
		.amdhsa_float_denorm_mode_32 3
		.amdhsa_float_denorm_mode_16_64 3
		.amdhsa_dx10_clamp 1
		.amdhsa_ieee_mode 1
		.amdhsa_fp16_overflow 0
		.amdhsa_tg_split 0
		.amdhsa_exception_fp_ieee_invalid_op 0
		.amdhsa_exception_fp_denorm_src 0
		.amdhsa_exception_fp_ieee_div_zero 0
		.amdhsa_exception_fp_ieee_overflow 0
		.amdhsa_exception_fp_ieee_underflow 0
		.amdhsa_exception_fp_ieee_inexact 0
		.amdhsa_exception_int_div_zero 0
	.end_amdhsa_kernel

; #define LAS __attribute__((address_space(3)))
; __global__ void __launch_bounds__(NTHR, 2) mega_fwd(Args A) {
;     extern __shared__ __attribute__((aligned(16))) unsigned char lds_raw[];
;     LAS unsigned char* lds = (LAS unsigned char*)lds_raw;
amdhsa.kernels:
  - .agpr_count:     0
    .args:
      - .offset:         0
        .size:           184
        .value_kind:     by_value
      - .offset:         184
        .size:           4
        .value_kind:     hidden_block_count_x
      - .offset:         188
        .size:           4
        .value_kind:     hidden_block_count_y
      - .offset:         192
        .size:           4
        .value_kind:     hidden_block_count_z
      - .offset:         196
        .size:           2
        .value_kind:     hidden_group_size_x
      - .offset:         198
        .size:           2
        .value_kind:     hidden_group_size_y
      - .offset:         200
        .size:           2
        .value_kind:     hidden_group_size_z
      - .offset:         202
        .size:           2
        .value_kind:     hidden_remainder_x
      - .offset:         204
        .size:           2
        .value_kind:     hidden_remainder_y
      - .offset:         206
        .size:           2
        .value_kind:     hidden_remainder_z
      - .offset:         224
        .size:           8
        .value_kind:     hidden_global_offset_x
      - .offset:         232
        .size:           8
        .value_kind:     hidden_global_offset_y
      - .offset:         240
        .size:           8
        .value_kind:     hidden_global_offset_z
      - .offset:         248
        .size:           2
        .value_kind:     hidden_grid_dims
      - .offset:         272
        .size:           8
        .value_kind:     hidden_multigrid_sync_arg
      - .offset:         304
        .size:           4
        .value_kind:     hidden_dynamic_lds_size
    .group_segment_fixed_size: 0
    .kernarg_segment_align: 8
    .kernarg_segment_size: 440
    .language:       OpenCL C
    .language_version:
      - 2
      - 0
    .max_flat_workgroup_size: 512
    .name:           _Z8mega_fwd4Args
    .private_segment_fixed_size: 0
    .sgpr_count:     108
    .sgpr_spill_count: 237
    .symbol:         _Z8mega_fwd4Args.kd
    .uniform_work_group_size: 1
    .uses_dynamic_stack: false
    .vgpr_count:     256
    .vgpr_spill_count: 0
    .wavefront_size: 64
